# attention tile loops: the s_setprio 1/0 toggles around the QK and PV MFMA blocks removed (8 sites)
# baseline (speedup 1.0000x reference)
.LBB0_584:
	s_add_i32 s10, s65, -1
	s_and_b32 s67, s10, 1
	s_sub_i32 s10, s66, 63
	s_cmp_gt_i32 s10, s49
	s_cbranch_scc1 .LBB0_597
	s_mul_i32 s10, s67, 0x3000
	v_add_u32_e32 v52, s10, v129
	ds_read_b128 v[48:51], v52
	ds_read_b128 v[192:195], v52 offset:512
	ds_read_b128 v[196:199], v52 offset:2048
	ds_read_b128 v[200:203], v52 offset:2560
	ds_read_b128 v[204:207], v52 offset:4096
	ds_read_b128 v[208:211], v52 offset:4608
	ds_read_b128 v[212:215], v52 offset:6144
	ds_read_b128 v[216:219], v52 offset:6656
	ds_read_b128 v[220:223], v52 offset:8192
	ds_read_b128 v[224:227], v52 offset:8704
	ds_read_b128 v[228:231], v52 offset:10240
	ds_read_b128 v[232:235], v52 offset:10752
	s_waitcnt lgkmcnt(11)
	v_mfma_f32_32x32x16_bf16 v[64:79], v[48:51], v[100:103], v[32:47]
	s_waitcnt lgkmcnt(9)
	v_mfma_f32_32x32x16_bf16 v[64:79], v[196:199], v[80:83], v[64:79]
	v_mfma_f32_32x32x16_bf16 v[48:63], v[192:195], v[100:103], v[32:47]
	s_waitcnt lgkmcnt(8)
	v_mfma_f32_32x32x16_bf16 v[48:63], v[200:203], v[80:83], v[48:63]
	s_waitcnt lgkmcnt(7)
	v_mfma_f32_32x32x16_bf16 v[64:79], v[204:207], v[84:87], v[64:79]
	s_waitcnt lgkmcnt(6)
	v_mfma_f32_32x32x16_bf16 v[48:63], v[208:211], v[84:87], v[48:63]
	s_waitcnt lgkmcnt(5)
	v_mfma_f32_32x32x16_bf16 v[64:79], v[212:215], v[88:91], v[64:79]
	s_waitcnt lgkmcnt(4)
	v_mfma_f32_32x32x16_bf16 v[48:63], v[216:219], v[88:91], v[48:63]
	s_waitcnt lgkmcnt(3)
	v_mfma_f32_32x32x16_bf16 v[64:79], v[220:223], v[92:95], v[64:79]
	s_waitcnt lgkmcnt(2)
	v_mfma_f32_32x32x16_bf16 v[48:63], v[224:227], v[92:95], v[48:63]
	s_waitcnt lgkmcnt(1)
	v_mfma_f32_32x32x16_bf16 v[64:79], v[228:231], v[96:99], v[64:79]
	s_waitcnt lgkmcnt(0)
	v_mfma_f32_32x32x16_bf16 v[48:63], v[232:235], v[96:99], v[48:63]
	s_cmp_le_i32 s66, s63
	s_cbranch_scc1 .LBB0_587
	v_add_u32_e32 v143, s66, v126
	v_subrev_u32_e32 v147, 31, v143
	v_subrev_u32_e32 v145, 63, v143
	v_cmp_le_i32_e32 vcc, v147, v182
	s_nop 4
	v_cndmask_b32_e32 v48, v135, v48, vcc
	v_cmp_lt_i32_e32 vcc, v145, v182
	s_nop 1
	v_cndmask_b32_e32 v65, v135, v65, vcc
	v_cmp_le_i32_e32 vcc, v145, v182
	v_subrev_u32_e32 v145, 30, v143
	s_nop 0
	v_cndmask_b32_e32 v64, v135, v64, vcc
	v_cmp_le_i32_e32 vcc, v145, v182
	v_subrev_u32_e32 v145, 61, v143
	s_nop 0
	v_cndmask_b32_e32 v49, v135, v49, vcc
	v_cmp_le_i32_e32 vcc, v145, v182
	v_subrev_u32_e32 v145, 29, v143
	s_nop 0
	v_cndmask_b32_e32 v66, v135, v66, vcc
	v_cmp_le_i32_e32 vcc, v145, v182
	v_subrev_u32_e32 v145, 60, v143
	s_nop 0
	v_cndmask_b32_e32 v50, v135, v50, vcc
	v_cmp_le_i32_e32 vcc, v145, v182
	v_subrev_u32_e32 v145, 28, v143
	s_nop 0
	v_cndmask_b32_e32 v67, v135, v67, vcc
	v_cmp_le_i32_e32 vcc, v145, v182
	v_subrev_u32_e32 v145, 55, v143
	s_nop 0
	v_cndmask_b32_e32 v51, v135, v51, vcc
	v_cmp_le_i32_e32 vcc, v145, v182
	v_subrev_u32_e32 v145, 23, v143
	s_nop 0
	v_cndmask_b32_e32 v68, v135, v68, vcc
	v_cmp_le_i32_e32 vcc, v145, v182
	v_subrev_u32_e32 v145, 54, v143
	s_nop 0
	v_cndmask_b32_e32 v52, v135, v52, vcc
	v_cmp_le_i32_e32 vcc, v145, v182
	v_subrev_u32_e32 v145, 22, v143
	s_nop 0
	v_cndmask_b32_e32 v69, v135, v69, vcc
	v_cmp_le_i32_e32 vcc, v145, v182
	v_subrev_u32_e32 v145, 53, v143
	s_nop 0
	v_cndmask_b32_e32 v53, v135, v53, vcc
	v_cmp_le_i32_e32 vcc, v145, v182
	v_subrev_u32_e32 v145, 21, v143
	s_nop 0
	v_cndmask_b32_e32 v70, v135, v70, vcc
	v_cmp_le_i32_e32 vcc, v145, v182
	v_subrev_u32_e32 v145, 52, v143
	s_nop 0
	v_cndmask_b32_e32 v54, v135, v54, vcc
	v_cmp_le_i32_e32 vcc, v145, v182
	v_subrev_u32_e32 v145, 20, v143
	s_nop 0
	v_cndmask_b32_e32 v71, v135, v71, vcc
	v_cmp_le_i32_e32 vcc, v145, v182
	v_subrev_u32_e32 v145, 47, v143
	s_nop 0
	v_cndmask_b32_e32 v55, v135, v55, vcc
	v_cmp_le_i32_e32 vcc, v145, v182
	v_add_u32_e32 v145, -15, v143
	s_nop 0
	v_cndmask_b32_e32 v72, v135, v72, vcc
	v_cmp_le_i32_e32 vcc, v145, v182
	v_subrev_u32_e32 v145, 46, v143
	s_nop 0
	v_cndmask_b32_e32 v56, v135, v56, vcc
	v_cmp_le_i32_e32 vcc, v145, v182
	v_add_u32_e32 v145, -14, v143
	s_nop 0
	v_cndmask_b32_e32 v73, v135, v73, vcc
	v_cmp_le_i32_e32 vcc, v145, v182
	v_subrev_u32_e32 v145, 45, v143
	s_nop 0
	v_cndmask_b32_e32 v57, v135, v57, vcc
	v_cmp_le_i32_e32 vcc, v145, v182
	v_add_u32_e32 v145, -13, v143
	s_nop 0
	v_cndmask_b32_e32 v74, v135, v74, vcc
	v_cmp_le_i32_e32 vcc, v145, v182
	v_subrev_u32_e32 v145, 44, v143
	s_nop 0
	v_cndmask_b32_e32 v58, v135, v58, vcc
	v_cmp_le_i32_e32 vcc, v145, v182
	v_add_u32_e32 v145, -12, v143
	s_nop 0
	v_cndmask_b32_e32 v75, v135, v75, vcc
	v_cmp_le_i32_e32 vcc, v145, v182
	v_subrev_u32_e32 v145, 39, v143
	s_nop 0
	v_cndmask_b32_e32 v59, v135, v59, vcc
	v_cmp_le_i32_e32 vcc, v145, v182
	v_add_u32_e32 v145, -7, v143
	s_nop 0
	v_cndmask_b32_e32 v76, v135, v76, vcc
	v_cmp_le_i32_e32 vcc, v145, v182
	v_subrev_u32_e32 v145, 38, v143
	s_nop 0
	v_cndmask_b32_e32 v60, v135, v60, vcc
	v_cmp_le_i32_e32 vcc, v145, v182
	v_add_u32_e32 v145, -6, v143
	s_nop 0
	v_cndmask_b32_e32 v77, v135, v77, vcc
	v_cmp_le_i32_e32 vcc, v145, v182
	v_subrev_u32_e32 v145, 37, v143
	s_nop 0
	v_cndmask_b32_e32 v61, v135, v61, vcc
	v_cmp_le_i32_e32 vcc, v145, v182
	v_add_u32_e32 v145, -5, v143
	s_nop 0
	v_cndmask_b32_e32 v78, v135, v78, vcc
	v_cmp_le_i32_e32 vcc, v145, v182
	v_subrev_u32_e32 v145, 36, v143
	v_add_u32_e32 v143, -4, v143
	v_cndmask_b32_e32 v62, v135, v62, vcc
	v_cmp_le_i32_e32 vcc, v145, v182
	s_nop 1
	v_cndmask_b32_e32 v79, v135, v79, vcc
	v_cmp_le_i32_e32 vcc, v143, v182
	s_nop 1
	v_cndmask_b32_e32 v63, v135, v63, vcc

.LBB0_596:
	v_exp_f32_e32 v192, v64
	v_exp_f32_e32 v193, v65
	v_exp_f32_e32 v196, v48
	v_exp_f32_e32 v197, v49
	v_exp_f32_e32 v194, v66
	v_exp_f32_e32 v195, v67
	v_exp_f32_e32 v198, v50
	v_exp_f32_e32 v199, v51
	v_exp_f32_e32 v200, v68
	v_exp_f32_e32 v201, v69
	v_pk_add_f32 v[48:49], v[196:197], v[192:193]
	v_exp_f32_e32 v202, v52
	v_exp_f32_e32 v203, v53
	v_pk_add_f32 v[48:49], v[194:195], v[48:49]
	v_exp_f32_e32 v204, v70
	v_exp_f32_e32 v205, v71
	v_pk_add_f32 v[48:49], v[198:199], v[48:49]
	v_exp_f32_e32 v206, v54
	v_exp_f32_e32 v207, v55
	v_pk_add_f32 v[48:49], v[200:201], v[48:49]
	v_exp_f32_e32 v208, v72
	v_exp_f32_e32 v209, v73
	v_pk_add_f32 v[48:49], v[202:203], v[48:49]
	v_exp_f32_e32 v210, v56
	v_exp_f32_e32 v211, v57
	v_pk_add_f32 v[48:49], v[204:205], v[48:49]
	v_exp_f32_e32 v212, v74
	v_exp_f32_e32 v213, v75
	v_pk_add_f32 v[48:49], v[206:207], v[48:49]
	v_exp_f32_e32 v214, v58
	v_exp_f32_e32 v215, v59
	v_pk_add_f32 v[48:49], v[208:209], v[48:49]
	v_exp_f32_e32 v216, v76
	v_exp_f32_e32 v217, v77
	v_pk_add_f32 v[48:49], v[210:211], v[48:49]
	v_exp_f32_e32 v218, v60
	v_exp_f32_e32 v219, v61
	v_pk_add_f32 v[48:49], v[212:213], v[48:49]
	v_exp_f32_e32 v220, v78
	v_exp_f32_e32 v221, v79
	v_pk_add_f32 v[48:49], v[214:215], v[48:49]
	v_exp_f32_e32 v222, v62
	v_exp_f32_e32 v223, v63
	v_pk_add_f32 v[48:49], v[216:217], v[48:49]
	s_mul_i32 s10, s67, 0x2200
	v_pk_add_f32 v[48:49], v[218:219], v[48:49]
	v_add_u32_e32 v232, s10, v238
	v_pk_add_f32 v[48:49], v[220:221], v[48:49]
	v_add_u32_e32 v233, s10, v239
	v_pk_add_f32 v[48:49], v[222:223], v[48:49]
	v_pk_add_f32 v[48:49], v[48:49], v[48:49] op_sel:[0,1] op_sel_hi:[1,0]
	v_cvt_pk_bf16_f32 v192, v192, v193
	v_mov_b32_e32 v49, v48
	s_nop 1
	v_permlane32_swap_b32_e32 v48, v49
	v_add_f32_e32 v143, v48, v49
	ds_read_b64_tr_b16 v[48:49], v232 offset:24576
	ds_read_b64_tr_b16 v[50:51], v232 offset:25600
	ds_read_b64_tr_b16 v[52:53], v232 offset:26624
	ds_read_b64_tr_b16 v[54:55], v232 offset:27648
	ds_read_b64_tr_b16 v[56:57], v233 offset:24576
	ds_read_b64_tr_b16 v[58:59], v233 offset:25600
	ds_read_b64_tr_b16 v[60:61], v233 offset:26624
	ds_read_b64_tr_b16 v[62:63], v233 offset:27648
	ds_read_b64_tr_b16 v[64:65], v232 offset:28672
	ds_read_b64_tr_b16 v[66:67], v232 offset:29696
	ds_read_b64_tr_b16 v[68:69], v233 offset:28672
	ds_read_b64_tr_b16 v[70:71], v233 offset:29696
	ds_read_b64_tr_b16 v[72:73], v232 offset:30720
	ds_read_b64_tr_b16 v[74:75], v232 offset:31744
	ds_read_b64_tr_b16 v[76:77], v233 offset:30720
	ds_read_b64_tr_b16 v[78:79], v233 offset:31744
	v_cvt_pk_bf16_f32 v193, v194, v195
	v_cvt_pk_bf16_f32 v194, v200, v201
	v_cvt_pk_bf16_f32 v195, v204, v205
	v_cvt_pk_bf16_f32 v196, v196, v197
	v_cvt_pk_bf16_f32 v197, v198, v199
	v_cvt_pk_bf16_f32 v198, v202, v203
	v_cvt_pk_bf16_f32 v199, v206, v207
	v_cvt_pk_bf16_f32 v200, v208, v209
	v_cvt_pk_bf16_f32 v201, v212, v213
	v_cvt_pk_bf16_f32 v202, v216, v217
	v_cvt_pk_bf16_f32 v203, v220, v221
	v_cvt_pk_bf16_f32 v204, v210, v211
	v_cvt_pk_bf16_f32 v205, v214, v215
	v_cvt_pk_bf16_f32 v206, v218, v219
	v_cvt_pk_bf16_f32 v207, v222, v223
	s_waitcnt lgkmcnt(14)
	v_mfma_f32_32x32x16_bf16 v[0:15], v[192:195], v[48:51], v[0:15]
	v_add_f32_e32 v139, v139, v143
	s_waitcnt lgkmcnt(10)
	v_mfma_f32_32x32x16_bf16 v[16:31], v[192:195], v[56:59], v[16:31]
	v_mfma_f32_32x32x16_bf16 v[0:15], v[200:203], v[52:55], v[0:15]
	s_waitcnt lgkmcnt(8)
	v_mfma_f32_32x32x16_bf16 v[16:31], v[200:203], v[60:63], v[16:31]
	s_waitcnt lgkmcnt(6)
	v_mfma_f32_32x32x16_bf16 v[0:15], v[196:199], v[64:67], v[0:15]
	s_waitcnt lgkmcnt(4)
	v_mfma_f32_32x32x16_bf16 v[16:31], v[196:199], v[68:71], v[16:31]
	s_waitcnt lgkmcnt(2)
	v_mfma_f32_32x32x16_bf16 v[0:15], v[204:207], v[72:75], v[0:15]
	s_waitcnt lgkmcnt(0)
	v_mfma_f32_32x32x16_bf16 v[16:31], v[204:207], v[76:79], v[16:31]

.LBB0_616:
	s_add_i32 s10, s63, -1
	s_and_b32 s65, s10, 1
	s_sub_i32 s10, s64, 63
	s_cmp_gt_i32 s10, s51
	s_cbranch_scc1 .LBB0_629
	s_mul_i32 s10, s65, 0x3000
	v_add_u32_e32 v52, s10, v129
	ds_read_b128 v[48:51], v52
	ds_read_b128 v[176:179], v52 offset:512
	ds_read_b128 v[184:187], v52 offset:2048
	ds_read_b128 v[192:195], v52 offset:2560
	ds_read_b128 v[196:199], v52 offset:4096
	ds_read_b128 v[200:203], v52 offset:4608
	ds_read_b128 v[204:207], v52 offset:6144
	ds_read_b128 v[208:211], v52 offset:6656
	ds_read_b128 v[212:215], v52 offset:8192
	ds_read_b128 v[216:219], v52 offset:8704
	ds_read_b128 v[220:223], v52 offset:10240
	ds_read_b128 v[224:227], v52 offset:10752
	s_waitcnt lgkmcnt(11)
	v_mfma_f32_32x32x16_bf16 v[64:79], v[48:51], v[100:103], v[32:47]
	s_waitcnt lgkmcnt(9)
	v_mfma_f32_32x32x16_bf16 v[64:79], v[184:187], v[80:83], v[64:79]
	v_mfma_f32_32x32x16_bf16 v[48:63], v[176:179], v[100:103], v[32:47]
	s_waitcnt lgkmcnt(8)
	v_mfma_f32_32x32x16_bf16 v[48:63], v[192:195], v[80:83], v[48:63]
	s_waitcnt lgkmcnt(7)
	v_mfma_f32_32x32x16_bf16 v[64:79], v[196:199], v[84:87], v[64:79]
	s_waitcnt lgkmcnt(6)
	v_mfma_f32_32x32x16_bf16 v[48:63], v[200:203], v[84:87], v[48:63]
	s_waitcnt lgkmcnt(5)
	v_mfma_f32_32x32x16_bf16 v[64:79], v[204:207], v[88:91], v[64:79]
	s_waitcnt lgkmcnt(4)
	v_mfma_f32_32x32x16_bf16 v[48:63], v[208:211], v[88:91], v[48:63]
	s_waitcnt lgkmcnt(3)
	v_mfma_f32_32x32x16_bf16 v[64:79], v[212:215], v[92:95], v[64:79]
	s_waitcnt lgkmcnt(2)
	v_mfma_f32_32x32x16_bf16 v[48:63], v[216:219], v[92:95], v[48:63]
	s_waitcnt lgkmcnt(1)
	v_mfma_f32_32x32x16_bf16 v[64:79], v[220:223], v[96:99], v[64:79]
	s_waitcnt lgkmcnt(0)
	v_mfma_f32_32x32x16_bf16 v[48:63], v[224:227], v[96:99], v[48:63]
	s_cmp_le_i32 s64, s47
	s_cbranch_scc1 .LBB0_619
	v_add_u32_e32 v145, s64, v126
	v_subrev_u32_e32 v149, 31, v145
	v_subrev_u32_e32 v147, 63, v145
	v_cmp_le_i32_e32 vcc, v149, v182
	s_nop 4
	v_cndmask_b32_e32 v48, v135, v48, vcc
	v_cmp_lt_i32_e32 vcc, v147, v182
	s_nop 1
	v_cndmask_b32_e32 v65, v135, v65, vcc
	v_cmp_le_i32_e32 vcc, v147, v182
	v_subrev_u32_e32 v147, 30, v145
	s_nop 0
	v_cndmask_b32_e32 v64, v135, v64, vcc
	v_cmp_le_i32_e32 vcc, v147, v182
	v_subrev_u32_e32 v147, 61, v145
	s_nop 0
	v_cndmask_b32_e32 v49, v135, v49, vcc
	v_cmp_le_i32_e32 vcc, v147, v182
	v_subrev_u32_e32 v147, 29, v145
	s_nop 0
	v_cndmask_b32_e32 v66, v135, v66, vcc
	v_cmp_le_i32_e32 vcc, v147, v182
	v_subrev_u32_e32 v147, 60, v145
	s_nop 0
	v_cndmask_b32_e32 v50, v135, v50, vcc
	v_cmp_le_i32_e32 vcc, v147, v182
	v_subrev_u32_e32 v147, 28, v145
	s_nop 0
	v_cndmask_b32_e32 v67, v135, v67, vcc
	v_cmp_le_i32_e32 vcc, v147, v182
	v_subrev_u32_e32 v147, 55, v145
	s_nop 0
	v_cndmask_b32_e32 v51, v135, v51, vcc
	v_cmp_le_i32_e32 vcc, v147, v182
	v_subrev_u32_e32 v147, 23, v145
	s_nop 0
	v_cndmask_b32_e32 v68, v135, v68, vcc
	v_cmp_le_i32_e32 vcc, v147, v182
	v_subrev_u32_e32 v147, 54, v145
	s_nop 0
	v_cndmask_b32_e32 v52, v135, v52, vcc
	v_cmp_le_i32_e32 vcc, v147, v182
	v_subrev_u32_e32 v147, 22, v145
	s_nop 0
	v_cndmask_b32_e32 v69, v135, v69, vcc
	v_cmp_le_i32_e32 vcc, v147, v182
	v_subrev_u32_e32 v147, 53, v145
	s_nop 0
	v_cndmask_b32_e32 v53, v135, v53, vcc
	v_cmp_le_i32_e32 vcc, v147, v182
	v_subrev_u32_e32 v147, 21, v145
	s_nop 0
	v_cndmask_b32_e32 v70, v135, v70, vcc
	v_cmp_le_i32_e32 vcc, v147, v182
	v_subrev_u32_e32 v147, 52, v145
	s_nop 0
	v_cndmask_b32_e32 v54, v135, v54, vcc
	v_cmp_le_i32_e32 vcc, v147, v182
	v_subrev_u32_e32 v147, 20, v145
	s_nop 0
	v_cndmask_b32_e32 v71, v135, v71, vcc
	v_cmp_le_i32_e32 vcc, v147, v182
	v_subrev_u32_e32 v147, 47, v145
	s_nop 0
	v_cndmask_b32_e32 v55, v135, v55, vcc
	v_cmp_le_i32_e32 vcc, v147, v182
	v_add_u32_e32 v147, -15, v145
	s_nop 0
	v_cndmask_b32_e32 v72, v135, v72, vcc
	v_cmp_le_i32_e32 vcc, v147, v182
	v_subrev_u32_e32 v147, 46, v145
	s_nop 0
	v_cndmask_b32_e32 v56, v135, v56, vcc
	v_cmp_le_i32_e32 vcc, v147, v182
	v_add_u32_e32 v147, -14, v145
	s_nop 0
	v_cndmask_b32_e32 v73, v135, v73, vcc
	v_cmp_le_i32_e32 vcc, v147, v182
	v_subrev_u32_e32 v147, 45, v145
	s_nop 0
	v_cndmask_b32_e32 v57, v135, v57, vcc
	v_cmp_le_i32_e32 vcc, v147, v182
	v_add_u32_e32 v147, -13, v145
	s_nop 0
	v_cndmask_b32_e32 v74, v135, v74, vcc
	v_cmp_le_i32_e32 vcc, v147, v182
	v_subrev_u32_e32 v147, 44, v145
	s_nop 0
	v_cndmask_b32_e32 v58, v135, v58, vcc
	v_cmp_le_i32_e32 vcc, v147, v182
	v_add_u32_e32 v147, -12, v145
	s_nop 0
	v_cndmask_b32_e32 v75, v135, v75, vcc
	v_cmp_le_i32_e32 vcc, v147, v182
	v_subrev_u32_e32 v147, 39, v145
	s_nop 0
	v_cndmask_b32_e32 v59, v135, v59, vcc
	v_cmp_le_i32_e32 vcc, v147, v182
	v_add_u32_e32 v147, -7, v145
	s_nop 0
	v_cndmask_b32_e32 v76, v135, v76, vcc
	v_cmp_le_i32_e32 vcc, v147, v182
	v_subrev_u32_e32 v147, 38, v145
	s_nop 0
	v_cndmask_b32_e32 v60, v135, v60, vcc
	v_cmp_le_i32_e32 vcc, v147, v182
	v_add_u32_e32 v147, -6, v145
	s_nop 0
	v_cndmask_b32_e32 v77, v135, v77, vcc
	v_cmp_le_i32_e32 vcc, v147, v182
	v_subrev_u32_e32 v147, 37, v145
	s_nop 0
	v_cndmask_b32_e32 v61, v135, v61, vcc
	v_cmp_le_i32_e32 vcc, v147, v182
	v_add_u32_e32 v147, -5, v145
	s_nop 0
	v_cndmask_b32_e32 v78, v135, v78, vcc
	v_cmp_le_i32_e32 vcc, v147, v182
	v_subrev_u32_e32 v147, 36, v145
	v_add_u32_e32 v145, -4, v145
	v_cndmask_b32_e32 v62, v135, v62, vcc
	v_cmp_le_i32_e32 vcc, v147, v182
	s_nop 1
	v_cndmask_b32_e32 v79, v135, v79, vcc
	v_cmp_le_i32_e32 vcc, v145, v182
	s_nop 1
	v_cndmask_b32_e32 v63, v135, v63, vcc

.LBB0_628:
	s_mul_i32 s10, s65, 0x2200
	v_add_u32_e32 v232, s10, v238
	v_add_u32_e32 v233, s10, v239
	ds_read_b64_tr_b16 v[212:213], v232 offset:24576
	ds_read_b64_tr_b16 v[214:215], v232 offset:25600
	ds_read_b64_tr_b16 v[216:217], v232 offset:26624
	ds_read_b64_tr_b16 v[218:219], v232 offset:27648
	ds_read_b64_tr_b16 v[220:221], v233 offset:24576
	ds_read_b64_tr_b16 v[222:223], v233 offset:25600
	ds_read_b64_tr_b16 v[224:225], v233 offset:26624
	ds_read_b64_tr_b16 v[226:227], v233 offset:27648
	ds_read_b64_tr_b16 v[228:229], v232 offset:28672
	ds_read_b64_tr_b16 v[230:231], v232 offset:29696
	v_exp_f32_e32 v176, v64
	v_exp_f32_e32 v177, v65
	v_exp_f32_e32 v180, v48
	v_exp_f32_e32 v181, v49
	v_exp_f32_e32 v178, v66
	v_exp_f32_e32 v179, v67
	v_exp_f32_e32 v186, v50
	v_exp_f32_e32 v187, v51
	v_exp_f32_e32 v184, v68
	v_exp_f32_e32 v185, v69
	v_pk_add_f32 v[48:49], v[180:181], v[176:177]
	v_exp_f32_e32 v188, v52
	v_exp_f32_e32 v189, v53
	v_pk_add_f32 v[48:49], v[178:179], v[48:49]
	v_exp_f32_e32 v192, v70
	v_exp_f32_e32 v193, v71
	v_pk_add_f32 v[48:49], v[186:187], v[48:49]
	v_exp_f32_e32 v194, v54
	v_exp_f32_e32 v195, v55
	v_pk_add_f32 v[48:49], v[184:185], v[48:49]
	v_exp_f32_e32 v196, v72
	v_exp_f32_e32 v197, v73
	v_pk_add_f32 v[48:49], v[188:189], v[48:49]
	v_exp_f32_e32 v198, v56
	v_exp_f32_e32 v199, v57
	v_pk_add_f32 v[48:49], v[192:193], v[48:49]
	v_exp_f32_e32 v200, v74
	v_exp_f32_e32 v201, v75
	v_pk_add_f32 v[48:49], v[194:195], v[48:49]
	v_exp_f32_e32 v202, v58
	v_exp_f32_e32 v203, v59
	v_pk_add_f32 v[48:49], v[196:197], v[48:49]
	v_exp_f32_e32 v204, v76
	v_exp_f32_e32 v205, v77
	v_pk_add_f32 v[48:49], v[198:199], v[48:49]
	v_exp_f32_e32 v206, v60
	v_exp_f32_e32 v207, v61
	v_pk_add_f32 v[48:49], v[200:201], v[48:49]
	v_exp_f32_e32 v208, v78
	v_exp_f32_e32 v209, v79
	v_pk_add_f32 v[48:49], v[202:203], v[48:49]
	v_exp_f32_e32 v210, v62
	v_exp_f32_e32 v211, v63
	v_pk_add_f32 v[48:49], v[204:205], v[48:49]
	v_pk_add_f32 v[48:49], v[206:207], v[48:49]
	v_pk_add_f32 v[48:49], v[208:209], v[48:49]
	v_pk_add_f32 v[48:49], v[210:211], v[48:49]
	v_pk_add_f32 v[48:49], v[48:49], v[48:49] op_sel:[0,1] op_sel_hi:[1,0]
	v_cvt_pk_bf16_f32 v176, v176, v177
	v_mov_b32_e32 v49, v48
	s_nop 1
	v_permlane32_swap_b32_e32 v48, v49
	v_add_f32_e32 v145, v48, v49
	ds_read_b64_tr_b16 v[68:69], v233 offset:28672
	ds_read_b64_tr_b16 v[70:71], v233 offset:29696
	ds_read_b64_tr_b16 v[72:73], v232 offset:30720
	ds_read_b64_tr_b16 v[74:75], v232 offset:31744
	ds_read_b64_tr_b16 v[76:77], v233 offset:30720
	ds_read_b64_tr_b16 v[78:79], v233 offset:31744
	v_cvt_pk_bf16_f32 v177, v178, v179
	v_cvt_pk_bf16_f32 v178, v184, v185
	v_cvt_pk_bf16_f32 v179, v192, v193
	v_cvt_pk_bf16_f32 v184, v180, v181
	v_cvt_pk_bf16_f32 v185, v186, v187
	v_cvt_pk_bf16_f32 v186, v188, v189
	v_cvt_pk_bf16_f32 v187, v194, v195
	v_cvt_pk_bf16_f32 v192, v196, v197
	v_cvt_pk_bf16_f32 v193, v200, v201
	v_cvt_pk_bf16_f32 v194, v204, v205
	v_cvt_pk_bf16_f32 v195, v208, v209
	v_cvt_pk_bf16_f32 v196, v198, v199
	v_cvt_pk_bf16_f32 v197, v202, v203
	v_cvt_pk_bf16_f32 v198, v206, v207
	v_cvt_pk_bf16_f32 v199, v210, v211
	s_waitcnt lgkmcnt(14)
	v_mfma_f32_32x32x16_bf16 v[0:15], v[176:179], v[212:215], v[0:15]
	v_add_f32_e32 v141, v141, v145
	s_waitcnt lgkmcnt(10)
	v_mfma_f32_32x32x16_bf16 v[16:31], v[176:179], v[220:223], v[16:31]
	v_mfma_f32_32x32x16_bf16 v[0:15], v[192:195], v[216:219], v[0:15]
	s_waitcnt lgkmcnt(8)
	v_mfma_f32_32x32x16_bf16 v[16:31], v[192:195], v[224:227], v[16:31]
	s_waitcnt lgkmcnt(6)
	v_mfma_f32_32x32x16_bf16 v[0:15], v[184:187], v[228:231], v[0:15]
	s_waitcnt lgkmcnt(4)
	v_mfma_f32_32x32x16_bf16 v[16:31], v[184:187], v[68:71], v[16:31]
	s_waitcnt lgkmcnt(2)
	v_mfma_f32_32x32x16_bf16 v[0:15], v[196:199], v[72:75], v[0:15]
	s_waitcnt lgkmcnt(0)
	v_mfma_f32_32x32x16_bf16 v[16:31], v[196:199], v[76:79], v[16:31]
